# fifth combination: fourth combination + fft table double buffering + P5 residual interleave + priority raise before K-loop barrier + GEMM1 LDS reads first
# baseline (speedup 1.0000x reference)
; #define PG8_STAGE(bufoff, gbase, voff) do { _Pragma("unroll") for (int _i = 0; _i < 2; ++_i) \
;         __builtin_amdgcn_global_load_lds((const unsigned*)((const char*)(gbase) + (voff)[_i]), (PG8_LAS unsigned*)(lds + (bufoff) + ldsw + _i * 8192), 16, 0, 0); } while (0)
; #define PG8_LDA(dst, b, h) do { _Pragma("unroll") for (int m = 0; m < 4; ++m) _Pragma("unroll") for (int k = 0; k < 2; ++k) dst[m][k] = *(const PG8_LAS bf16x8*)(lds + PG8_SA(b, h) + aoff + m * 2048 + k * 1024); } while (0)
; #define PG8_LDB(dst, b, h) do { _Pragma("unroll") for (int n = 0; n < 2; ++n) _Pragma("unroll") for (int k = 0; k < 2; ++k) dst[n][k] = *(const PG8_LAS bf16x8*)(lds + PG8_SB(b, h) + boff + n * 2048 + k * 1024); } while (0)
; #define PG8_MMA(ai, bj, At, Bt) do { __builtin_amdgcn_s_setprio(1); _Pragma("unroll") for (int m = 0; m < 4; ++m) _Pragma("unroll") for (int n = 0; n < 2; ++n) _Pragma("unroll") for (int k = 0; k < 2; ++k) \
;         acc[ai][bj][m][n] = Gemm::i8 ? ::mfma16i8_g(Bt[n][k], At[m][k], acc[ai][bj][m][n]) : ::mfma16_g(Bt[n][k], At[m][k], acc[ai][bj][m][n]); __builtin_amdgcn_s_setprio(0); } while (0)
; #define PG8_WAIT_V(n) asm volatile("s_waitcnt vmcnt(" #n ")" ::: "memory")
; #define PG8_WAIT_L(n) asm volatile("s_waitcnt lgkmcnt(" #n ")" ::: "memory")
; template <class Epi, class Sched, class Gemm, bool ALIGN_EPI = false, bool SP2 = false>
; __device__ __forceinline__ void gemm_phase(PG8_LAS unsigned char* lds, const Gemm g, const Sched& S, const Epi& E) {
;     ...
;             PG8_LDB(B0, 0, 0); PG8_LDB(B1, 0, 1); PG8_SCHED; PG8_LDA(At, 0, 0); PG8_STAGE(PG8_SA(1, 1), a1 + hstepA, voffA);
;             PG8_WAIT_V(8); PG8_WAIT_L(0); PG8_BAR; PG8_MMA(0, 0, At, B0); PG8_MMA(0, 1, At, B1); PG8_BAR; PG8_SCHED;
;             PG8_LDA(At, 0, 1); PG8_STAGE(PG8_SB(0, 0), b2, voffB); PG8_STAGE(PG8_SB(0, 1), b2 + hB1, voffB1); PG8_STAGE(PG8_SA(0, 0), a2, voffA);
;             PG8_WAIT_V(8); PG8_WAIT_L(0); PG8_BAR; PG8_MMA(1, 0, At, B0); PG8_MMA(1, 1, At, B1); PG8_BAR; PG8_SCHED;
;             PG8_LDB(B0, 1, 0); PG8_LDB(B1, 1, 1); PG8_SCHED; PG8_LDA(At, 1, 0); PG8_STAGE(PG8_SA(0, 1), a2 + hstepA, voffA);
;             PG8_WAIT_V(8); PG8_WAIT_L(0); PG8_BAR; PG8_MMA(0, 0, At, B0); PG8_MMA(0, 1, At, B1); PG8_BAR; PG8_SCHED;
;             PG8_LDA(At, 1, 1); PG8_STAGE(PG8_SB(1, 0), b3, voffB); PG8_STAGE(PG8_SB(1, 1), b3 + hB1, voffB1); PG8_STAGE(PG8_SA(1, 0), a3, voffA);
.LBB0_136:
	ds_read_b128 v[174:177], v253
	ds_read_b128 v[170:173], v253 offset:1024
	ds_read_b128 v[166:169], v253 offset:2048
	ds_read_b128 v[162:165], v253 offset:3072
	ds_read_b128 v[158:161], v254
	ds_read_b128 v[154:157], v254 offset:1024
	ds_read_b128 v[150:153], v254 offset:2048
	ds_read_b128 v[146:149], v254 offset:3072
	ds_read_b128 v[190:193], v222
	ds_read_b128 v[194:197], v222 offset:1024
	ds_read_b128 v[198:201], v222 offset:2048
	ds_read_b128 v[202:205], v222 offset:3072
	ds_read_b128 v[206:209], v222 offset:4096
	ds_read_b128 v[186:189], v222 offset:5120
	ds_read_b128 v[182:185], v222 offset:6144
	ds_read_b128 v[178:181], v222 offset:7168
	s_add_u32 s0, s48, 0xfffe0080
	s_addc_u32 s1, s49, -1
	s_cmp_eq_u32 s2, 4
	s_cselect_b32 s53, s7, s1
	s_cselect_b32 s52, s43, s0
	s_cselect_b32 s55, s79, s82
	s_cselect_b32 s54, s80, s81
	s_add_i32 s95, s76, s64
	s_add_i32 m0, s65, 0xc000
	s_add_i32 s96, s65, 0xe000
	s_add_i32 s92, s95, 0x2000
	s_add_u32 s56, s54, 0x20000
	s_addc_u32 s57, s55, 0
	s_add_i32 s94, s77, s64
	s_add_i32 s93, s94, 0x2000
	s_add_i32 s91, 0, 0x18000
	s_add_i32 s90, 0, 0x1c000
	s_add_u32 s50, s52, 0x20000
	s_addc_u32 s51, s53, 0
	s_add_i32 s83, s91, s64
	s_add_i32 s3, s83, 0x2000
	s_add_u32 s0, s54, 0x20080
	s_addc_u32 s1, s55, 0
	s_add_i32 s89, s90, s64
	s_add_i32 s88, s89, 0x2000
	s_cmp_lg_u32 s2, 4
	global_load_lds_dwordx4 v220, s[48:49]
	s_mov_b32 m0, s96
	s_nop 0
	global_load_lds_dwordx4 v218, s[48:49]
	s_waitcnt vmcnt(8)
	s_waitcnt lgkmcnt(0)
	s_nop 0
	s_setprio 1
	s_barrier
	v_mfma_i32_16x16x64_i8 v[142:145], v[174:177], v[190:193], v[142:145]
	v_mfma_i32_16x16x64_i8 v[138:141], v[166:169], v[190:193], v[138:141]
	v_mfma_i32_16x16x64_i8 v[126:129], v[174:177], v[198:201], v[126:129]
	v_mfma_i32_16x16x64_i8 v[122:125], v[166:169], v[198:201], v[122:125]
	v_mfma_i32_16x16x64_i8 v[110:113], v[174:177], v[206:209], v[110:113]
	v_mfma_i32_16x16x64_i8 v[106:109], v[166:169], v[206:209], v[106:109]
	v_mfma_i32_16x16x64_i8 v[94:97], v[174:177], v[182:185], v[94:97]
	v_mfma_i32_16x16x64_i8 v[90:93], v[166:169], v[182:185], v[90:93]
	v_mfma_i32_16x16x64_i8 v[142:145], v[170:173], v[194:197], v[142:145]
	v_mfma_i32_16x16x64_i8 v[138:141], v[162:165], v[194:197], v[138:141]
	v_mfma_i32_16x16x64_i8 v[126:129], v[170:173], v[202:205], v[126:129]
	v_mfma_i32_16x16x64_i8 v[122:125], v[162:165], v[202:205], v[122:125]
	v_mfma_i32_16x16x64_i8 v[110:113], v[170:173], v[186:189], v[110:113]
	v_mfma_i32_16x16x64_i8 v[106:109], v[162:165], v[186:189], v[106:109]
	v_mfma_i32_16x16x64_i8 v[94:97], v[170:173], v[178:181], v[94:97]
	v_mfma_i32_16x16x64_i8 v[90:93], v[162:165], v[178:181], v[90:93]
	s_setprio 0
	s_setprio 1
	v_mfma_i32_16x16x64_i8 v[134:137], v[158:161], v[190:193], v[134:137]
	v_mfma_i32_16x16x64_i8 v[130:133], v[150:153], v[190:193], v[130:133]
	v_mfma_i32_16x16x64_i8 v[118:121], v[158:161], v[198:201], v[118:121]
	v_mfma_i32_16x16x64_i8 v[114:117], v[150:153], v[198:201], v[114:117]
	v_mfma_i32_16x16x64_i8 v[102:105], v[158:161], v[206:209], v[102:105]
	v_mfma_i32_16x16x64_i8 v[98:101], v[150:153], v[206:209], v[98:101]
	v_mfma_i32_16x16x64_i8 v[86:89], v[158:161], v[182:185], v[86:89]
	v_mfma_i32_16x16x64_i8 v[82:85], v[150:153], v[182:185], v[82:85]
	v_mfma_i32_16x16x64_i8 v[134:137], v[154:157], v[194:197], v[134:137]
	v_mfma_i32_16x16x64_i8 v[130:133], v[146:149], v[194:197], v[130:133]
	v_mfma_i32_16x16x64_i8 v[118:121], v[154:157], v[202:205], v[118:121]
	v_mfma_i32_16x16x64_i8 v[114:117], v[146:149], v[202:205], v[114:117]
	v_mfma_i32_16x16x64_i8 v[102:105], v[154:157], v[186:189], v[102:105]
	v_mfma_i32_16x16x64_i8 v[98:101], v[146:149], v[186:189], v[98:101]
	v_mfma_i32_16x16x64_i8 v[86:89], v[154:157], v[178:181], v[86:89]
	v_mfma_i32_16x16x64_i8 v[82:85], v[146:149], v[178:181], v[82:85]
	s_setprio 0
	s_barrier
	s_mov_b32 m0, s95
	v_lshl_add_u64 v[242:243], s[54:55], 0, v[212:213]
	ds_read_b128 v[190:193], v222 offset:16384
	ds_read_b128 v[194:197], v222 offset:17408
	ds_read_b128 v[198:201], v222 offset:18432
	ds_read_b128 v[202:205], v222 offset:19456
	ds_read_b128 v[206:209], v222 offset:20480
	ds_read_b128 v[186:189], v222 offset:21504
	ds_read_b128 v[182:185], v222 offset:22528
	ds_read_b128 v[178:181], v222 offset:23552
	global_load_lds_dwordx4 v212, s[54:55]
	v_lshl_add_u64 v[244:245], s[54:55], 0, v[216:217]
	s_mov_b32 m0, s92
	v_lshl_add_u64 v[246:247], s[56:57], 0, v[212:213]
	global_load_lds_dwordx4 v216, s[54:55]
	s_mov_b32 m0, s94
	v_lshl_add_u64 v[248:249], s[52:53], 0, v[214:215]
	global_load_lds_dwordx4 v212, s[56:57]
	s_mov_b32 m0, s93
	s_nop 0
	global_load_lds_dwordx4 v216, s[56:57]
	v_lshl_add_u64 v[246:247], s[52:53], 0, v[210:211]
	s_mov_b32 m0, s65
	s_nop 0
	global_load_lds_dwordx4 v210, s[52:53]
	s_mov_b32 m0, s66
	s_nop 0
	global_load_lds_dwordx4 v214, s[52:53]
	s_waitcnt vmcnt(8)
	s_waitcnt lgkmcnt(0)
	s_nop 0
	s_setprio 1
	s_barrier
; #define PG8_STAGE(bufoff, gbase, voff) do { _Pragma("unroll") for (int _i = 0; _i < 2; ++_i) \
;         __builtin_amdgcn_global_load_lds((const unsigned*)((const char*)(gbase) + (voff)[_i]), (PG8_LAS unsigned*)(lds + (bufoff) + ldsw + _i * 8192), 16, 0, 0); } while (0)
; #define PG8_LDA(dst, b, h) do { _Pragma("unroll") for (int m = 0; m < 4; ++m) _Pragma("unroll") for (int k = 0; k < 2; ++k) dst[m][k] = *(const PG8_LAS bf16x8*)(lds + PG8_SA(b, h) + aoff + m * 2048 + k * 1024); } while (0)
; #define PG8_LDB(dst, b, h) do { _Pragma("unroll") for (int n = 0; n < 2; ++n) _Pragma("unroll") for (int k = 0; k < 2; ++k) dst[n][k] = *(const PG8_LAS bf16x8*)(lds + PG8_SB(b, h) + boff + n * 2048 + k * 1024); } while (0)
; #define PG8_MMA(ai, bj, At, Bt) do { __builtin_amdgcn_s_setprio(1); _Pragma("unroll") for (int m = 0; m < 4; ++m) _Pragma("unroll") for (int n = 0; n < 2; ++n) _Pragma("unroll") for (int k = 0; k < 2; ++k) \
;         acc[ai][bj][m][n] = Gemm::i8 ? ::mfma16i8_g(Bt[n][k], At[m][k], acc[ai][bj][m][n]) : ::mfma16_g(Bt[n][k], At[m][k], acc[ai][bj][m][n]); __builtin_amdgcn_s_setprio(0); } while (0)
; #define PG8_WAIT_V(n) asm volatile("s_waitcnt vmcnt(" #n ")" ::: "memory")
; #define PG8_WAIT_L(n) asm volatile("s_waitcnt lgkmcnt(" #n ")" ::: "memory")
; template <class Epi, class Sched, class Gemm, bool ALIGN_EPI = false, bool SP2 = false>
; __device__ __forceinline__ void gemm_phase(PG8_LAS unsigned char* lds, const Gemm g, const Sched& S, const Epi& E) {
;     ...
;             PG8_LDB(B0, 0, 0); PG8_LDB(B1, 0, 1); PG8_SCHED; PG8_LDA(At, 0, 0); PG8_STAGE(PG8_SA(1, 1), a1 + hstepA, voffA);
;             PG8_WAIT_V(8); PG8_WAIT_L(0); PG8_BAR; PG8_MMA(0, 0, At, B0); PG8_MMA(0, 1, At, B1); PG8_BAR; PG8_SCHED;
;             PG8_LDA(At, 0, 1); PG8_STAGE(PG8_SB(0, 0), b2, voffB); PG8_STAGE(PG8_SB(0, 1), b2 + hB1, voffB1); PG8_STAGE(PG8_SA(0, 0), a2, voffA);
;             PG8_WAIT_V(8); PG8_WAIT_L(0); PG8_BAR; PG8_MMA(1, 0, At, B0); PG8_MMA(1, 1, At, B1); PG8_BAR; PG8_SCHED;
;             PG8_LDB(B0, 1, 0); PG8_LDB(B1, 1, 1); PG8_SCHED; PG8_LDA(At, 1, 0); PG8_STAGE(PG8_SA(0, 1), a2 + hstepA, voffA);
;             PG8_WAIT_V(8); PG8_WAIT_L(0); PG8_BAR; PG8_MMA(0, 0, At, B0); PG8_MMA(0, 1, At, B1); PG8_BAR; PG8_SCHED;
;             PG8_LDA(At, 1, 1); PG8_STAGE(PG8_SB(1, 0), b3, voffB); PG8_STAGE(PG8_SB(1, 1), b3 + hB1, voffB1); PG8_STAGE(PG8_SA(1, 0), a3, voffA);
	v_mfma_i32_16x16x64_i8 v[78:81], v[174:177], v[190:193], v[78:81]
	v_mfma_i32_16x16x64_i8 v[74:77], v[166:169], v[190:193], v[74:77]
	v_mfma_i32_16x16x64_i8 v[62:65], v[174:177], v[198:201], v[62:65]
	v_mfma_i32_16x16x64_i8 v[58:61], v[166:169], v[198:201], v[58:61]
	v_mfma_i32_16x16x64_i8 v[46:49], v[174:177], v[206:209], v[46:49]
	v_mfma_i32_16x16x64_i8 v[42:45], v[166:169], v[206:209], v[42:45]
	v_mfma_i32_16x16x64_i8 v[30:33], v[174:177], v[182:185], v[30:33]
	v_mfma_i32_16x16x64_i8 v[26:29], v[166:169], v[182:185], v[26:29]
	v_mfma_i32_16x16x64_i8 v[78:81], v[170:173], v[194:197], v[78:81]
	v_mfma_i32_16x16x64_i8 v[74:77], v[162:165], v[194:197], v[74:77]
	v_mfma_i32_16x16x64_i8 v[62:65], v[170:173], v[202:205], v[62:65]
	v_mfma_i32_16x16x64_i8 v[58:61], v[162:165], v[202:205], v[58:61]
	v_mfma_i32_16x16x64_i8 v[46:49], v[170:173], v[186:189], v[46:49]
	v_mfma_i32_16x16x64_i8 v[42:45], v[162:165], v[186:189], v[42:45]
	v_mfma_i32_16x16x64_i8 v[30:33], v[170:173], v[178:181], v[30:33]
	v_mfma_i32_16x16x64_i8 v[26:29], v[162:165], v[178:181], v[26:29]
	s_setprio 0
	s_setprio 1
	v_mfma_i32_16x16x64_i8 v[70:73], v[158:161], v[190:193], v[70:73]
	v_mfma_i32_16x16x64_i8 v[66:69], v[150:153], v[190:193], v[66:69]
	v_mfma_i32_16x16x64_i8 v[54:57], v[158:161], v[198:201], v[54:57]
	v_mfma_i32_16x16x64_i8 v[50:53], v[150:153], v[198:201], v[50:53]
	v_mfma_i32_16x16x64_i8 v[38:41], v[158:161], v[206:209], v[38:41]
	v_mfma_i32_16x16x64_i8 v[34:37], v[150:153], v[206:209], v[34:37]
	v_mfma_i32_16x16x64_i8 v[22:25], v[158:161], v[182:185], v[22:25]
	v_mfma_i32_16x16x64_i8 v[18:21], v[150:153], v[182:185], v[18:21]
	v_mfma_i32_16x16x64_i8 v[70:73], v[154:157], v[194:197], v[70:73]
	v_mfma_i32_16x16x64_i8 v[66:69], v[146:149], v[194:197], v[66:69]
	v_mfma_i32_16x16x64_i8 v[54:57], v[154:157], v[202:205], v[54:57]
	v_mfma_i32_16x16x64_i8 v[50:53], v[146:149], v[202:205], v[50:53]
	v_mfma_i32_16x16x64_i8 v[38:41], v[154:157], v[186:189], v[38:41]
	v_mfma_i32_16x16x64_i8 v[34:37], v[146:149], v[186:189], v[34:37]
	v_mfma_i32_16x16x64_i8 v[22:25], v[154:157], v[178:181], v[22:25]
	v_mfma_i32_16x16x64_i8 v[18:21], v[146:149], v[178:181], v[18:21]
	s_setprio 0
	s_barrier
	v_add_u32_e32 v146, s91, v251
	ds_read_b128 v[174:177], v146
	ds_read_b128 v[170:173], v146 offset:1024
	ds_read_b128 v[166:169], v146 offset:2048
	ds_read_b128 v[162:165], v146 offset:3072
	v_add_u32_e32 v146, s90, v251
	ds_read_b128 v[150:153], v146
	ds_read_b128 v[154:157], v146 offset:1024
	ds_read_b128 v[158:161], v146 offset:2048
	ds_read_b128 v[146:149], v146 offset:3072
	s_mov_b32 m0, s67
	ds_read_b128 v[190:193], v222 offset:32768
	ds_read_b128 v[194:197], v222 offset:33792
	ds_read_b128 v[198:201], v222 offset:34816
	ds_read_b128 v[202:205], v222 offset:35840
	ds_read_b128 v[206:209], v222 offset:36864
	ds_read_b128 v[186:189], v222 offset:37888
	ds_read_b128 v[182:185], v222 offset:38912
	ds_read_b128 v[178:181], v222 offset:39936
	global_load_lds_dwordx4 v210, s[50:51]
	s_mov_b32 m0, s68
	s_nop 0
	global_load_lds_dwordx4 v214, s[50:51]
	s_waitcnt vmcnt(8)
	s_waitcnt lgkmcnt(0)
	s_nop 0
	s_setprio 1
	s_barrier
	v_mfma_i32_16x16x64_i8 v[142:145], v[174:177], v[190:193], v[142:145]
	v_mfma_i32_16x16x64_i8 v[138:141], v[166:169], v[190:193], v[138:141]
	v_mfma_i32_16x16x64_i8 v[126:129], v[174:177], v[198:201], v[126:129]
	v_mfma_i32_16x16x64_i8 v[122:125], v[166:169], v[198:201], v[122:125]
	v_mfma_i32_16x16x64_i8 v[110:113], v[174:177], v[206:209], v[110:113]
	v_mfma_i32_16x16x64_i8 v[106:109], v[166:169], v[206:209], v[106:109]
	v_mfma_i32_16x16x64_i8 v[94:97], v[174:177], v[182:185], v[94:97]
	v_mfma_i32_16x16x64_i8 v[90:93], v[166:169], v[182:185], v[90:93]
	v_mfma_i32_16x16x64_i8 v[142:145], v[170:173], v[194:197], v[142:145]
	v_mfma_i32_16x16x64_i8 v[138:141], v[162:165], v[194:197], v[138:141]
	v_mfma_i32_16x16x64_i8 v[126:129], v[170:173], v[202:205], v[126:129]
	v_mfma_i32_16x16x64_i8 v[122:125], v[162:165], v[202:205], v[122:125]
	v_mfma_i32_16x16x64_i8 v[110:113], v[170:173], v[186:189], v[110:113]
	v_mfma_i32_16x16x64_i8 v[106:109], v[162:165], v[186:189], v[106:109]
	v_mfma_i32_16x16x64_i8 v[94:97], v[170:173], v[178:181], v[94:97]
	v_mfma_i32_16x16x64_i8 v[90:93], v[162:165], v[178:181], v[90:93]
	s_setprio 0
	s_setprio 1
	v_mfma_i32_16x16x64_i8 v[134:137], v[150:153], v[190:193], v[134:137]
	v_mfma_i32_16x16x64_i8 v[130:133], v[158:161], v[190:193], v[130:133]
	v_mfma_i32_16x16x64_i8 v[118:121], v[150:153], v[198:201], v[118:121]
	v_mfma_i32_16x16x64_i8 v[114:117], v[158:161], v[198:201], v[114:117]
	v_mfma_i32_16x16x64_i8 v[102:105], v[150:153], v[206:209], v[102:105]
	v_mfma_i32_16x16x64_i8 v[98:101], v[158:161], v[206:209], v[98:101]
	v_mfma_i32_16x16x64_i8 v[86:89], v[150:153], v[182:185], v[86:89]
	v_mfma_i32_16x16x64_i8 v[82:85], v[158:161], v[182:185], v[82:85]
	v_mfma_i32_16x16x64_i8 v[134:137], v[154:157], v[194:197], v[134:137]
	v_mfma_i32_16x16x64_i8 v[130:133], v[146:149], v[194:197], v[130:133]
	v_mfma_i32_16x16x64_i8 v[118:121], v[154:157], v[202:205], v[118:121]
	v_mfma_i32_16x16x64_i8 v[114:117], v[146:149], v[202:205], v[114:117]
	v_mfma_i32_16x16x64_i8 v[102:105], v[154:157], v[186:189], v[102:105]
	v_mfma_i32_16x16x64_i8 v[98:101], v[146:149], v[186:189], v[98:101]
	v_mfma_i32_16x16x64_i8 v[86:89], v[154:157], v[178:181], v[86:89]
	v_mfma_i32_16x16x64_i8 v[82:85], v[146:149], v[178:181], v[82:85]
	s_setprio 0
	s_barrier
	s_mov_b32 m0, s83
	v_lshl_add_u64 v[224:225], v[242:243], 0, s[36:37]
	ds_read_b128 v[206:209], v222 offset:49152
	ds_read_b128 v[202:205], v222 offset:50176
	ds_read_b128 v[194:197], v222 offset:51200
	ds_read_b128 v[198:201], v222 offset:52224
	ds_read_b128 v[186:189], v222 offset:53248
	ds_read_b128 v[190:193], v222 offset:54272
	ds_read_b128 v[182:185], v222 offset:55296
	ds_read_b128 v[178:181], v222 offset:56320
	global_load_lds_dwordx4 v[224:225], off
	v_lshl_add_u64 v[224:225], v[244:245], 0, s[36:37]
	s_mov_b32 m0, s3
	s_nop 0
	global_load_lds_dwordx4 v[224:225], off
	s_mov_b32 m0, s89
	s_nop 0
	global_load_lds_dwordx4 v212, s[0:1]
	s_mov_b32 m0, s88
	s_nop 0
	global_load_lds_dwordx4 v216, s[0:1]
	v_lshl_add_u64 v[224:225], v[246:247], 0, s[36:37]
	s_mov_b32 m0, s72
	s_nop 0
	global_load_lds_dwordx4 v[224:225], off
	v_lshl_add_u64 v[224:225], v[248:249], 0, s[36:37]
	s_mov_b32 m0, s73
	s_nop 0
	global_load_lds_dwordx4 v[224:225], off
	s_waitcnt vmcnt(8)
	s_cbranch_scc1 .LBB0_135
	s_branch .LBB0_135
